# v12 + EpiQK epilogue: 8 row-stat loads hoisted, counted vmcnt
# baseline (speedup 1.0000x reference)
; __device__ __forceinline__ u32x2 pack4(f32x4 v) { u32x2 w; w.x = cvt_pk_bf16(v[0], v[1]); w.y = cvt_pk_bf16(v[2], v[3]); return w; }
; __device__ __forceinline__ float rstd_row4(const float* ssrow, int fq) { const f32x4 a = *(const f32x4*)(ssrow + 4 * fq); float ss = (a[0] + a[1]) + (a[2] + a[3]);
;     ss += __shfl_xor(ss, 16); ss += __shfl_xor(ss, 32); return __builtin_amdgcn_rsqf(ss * (1.0f / 1024.0f) + 1e-6f); }
;     __device__ __forceinline__ void operator()(const f32x4 (&acc)[2][2][4][2], const Unit& u, int wr, int wc, int fr, int fq) const {
;     ...
;         for (int ai = 0; ai < 2; ++ai)
; #pragma unroll
;             for (int m = 0; m < 4; ++m) {
;                 const int row = u.pm * BM + ai * HALF + wr * 64 + m * 16 + fr; const float rs = rstd_row4(ss + (size_t)row * 16, fq);
;                 bf16_t* rowp = base + (size_t)row * 1024 + cc;
; #pragma unroll
;                 for (int bj = 0; bj < 2; ++bj) { const f32x4 v0 = acc[ai][bj][m][0] * rs, v1 = acc[ai][bj][m][1] * rs; const u32x2 p0 = pack4(v0), p1 = pack4(v1);
;                     u32x4 w; w.x = p0.x; w.y = p0.y; w.z = p1.x; w.w = p1.y; *(u32x4*)(rowp + bj * HALF) = w; cs[bj][0] = cs[bj][0] + v0; cs[bj][1] = cs[bj][1] + v1; }
.LBB0_371:
	v_lshl_add_u32 v156, s28, 8, v158
	v_ashrrev_i32_e32 v157, 31, v156
	v_lshlrev_b64 v[166:167], 6, v[156:157]
	v_lshl_add_u64 v[166:167], v[136:137], 0, v[166:167]
	v_mov_b32_e32 v224, v166
	v_mov_b32_e32 v225, v167
	global_load_dwordx4 v[166:169], v[166:167], off
	global_load_dwordx4 v[176:179], v[224:225], off offset:1024
	global_load_dwordx4 v[180:183], v[224:225], off offset:2048
	global_load_dwordx4 v[184:187], v[224:225], off offset:3072
	v_lshl_add_u64 v[226:227], v[150:151], 4, v[224:225]
	global_load_dwordx4 v[188:191], v[226:227], off
	global_load_dwordx4 v[192:195], v[226:227], off offset:1024
	global_load_dwordx4 v[196:199], v[226:227], off offset:2048
	global_load_dwordx4 v[216:219], v[226:227], off offset:3072
	s_cmp_lt_i32 s42, 4
	v_and_b32_e32 v143, 64, v203
	s_cselect_b64 s[40:41], -1, 0
	v_xor_b32_e32 v142, 16, v203
	v_add_u32_e32 v163, 64, v143
	s_and_b64 s[44:45], s[40:41], exec
	v_cmp_lt_i32_e32 vcc, v142, v163
	s_cselect_b32 s45, s81, s83
	s_cselect_b32 s44, s80, s82
	s_lshl_b32 s13, s42, 8
	v_cndmask_b32_e32 v142, v203, v142, vcc
	s_and_b32 s13, s13, 0x300
	v_lshlrev_b32_e32 v164, 2, v142
	v_xor_b32_e32 v142, 32, v203
	v_or_b32_e32 v162, s13, v160
	v_cmp_lt_i32_e32 vcc, v142, v163
	v_lshlrev_b32_e32 v144, 1, v162
	s_or_b64 s[40:41], s[6:7], s[40:41]
	v_cndmask_b32_e32 v142, v203, v142, vcc
	v_lshlrev_b32_e32 v165, 2, v142
	v_lshl_add_u64 v[142:143], s[44:45], 0, v[144:145]
	s_and_b64 vcc, exec, s[40:41]
	s_waitcnt vmcnt(7)
	v_add_f32_e32 v170, v166, v167
	v_add_f32_e32 v171, v168, v169
	v_add_f32_e32 v144, v170, v171
	ds_bpermute_b32 v166, v164, v144
	s_waitcnt lgkmcnt(0)
	v_add_f32_e32 v144, v144, v166
	ds_bpermute_b32 v166, v165, v144
	s_waitcnt lgkmcnt(0)
	v_add_f32_e32 v144, v144, v166
	v_fmamk_f32 v144, v144, 0x3a800000, v201
	v_rsq_f32_e32 v144, v144
	v_lshlrev_b64 v[166:167], 11, v[156:157]
	v_lshl_add_u64 v[170:171], v[142:143], 0, v[166:167]
	v_pk_mul_f32 v[126:127], v[126:127], v[144:145] op_sel_hi:[1,0]
	v_pk_mul_f32 v[124:125], v[124:125], v[144:145] op_sel_hi:[1,0]
	v_pk_mul_f32 v[122:123], v[122:123], v[144:145] op_sel_hi:[1,0]
	v_pk_mul_f32 v[120:121], v[120:121], v[144:145] op_sel_hi:[1,0]
	v_cvt_pk_bf16_f32 v166, v124, v125
	v_cvt_pk_bf16_f32 v167, v126, v127
	v_cvt_pk_bf16_f32 v168, v120, v121
	v_cvt_pk_bf16_f32 v169, v122, v123
	v_pk_mul_f32 v[118:119], v[118:119], v[144:145] op_sel_hi:[1,0]
	v_pk_mul_f32 v[116:117], v[116:117], v[144:145] op_sel_hi:[1,0]
	v_pk_mul_f32 v[114:115], v[114:115], v[144:145] op_sel_hi:[1,0]
	v_pk_mul_f32 v[112:113], v[112:113], v[144:145] op_sel_hi:[1,0]
	global_store_dwordx4 v[170:171], v[166:169], off
	s_nop 1
	v_cvt_pk_bf16_f32 v166, v116, v117
	v_cvt_pk_bf16_f32 v167, v118, v119
	v_cvt_pk_bf16_f32 v168, v112, v113
	v_cvt_pk_bf16_f32 v169, v114, v115
	global_store_dwordx4 v[170:171], v[166:169], off offset:256
	v_or_b32_e32 v170, 16, v156
	v_ashrrev_i32_e32 v171, 31, v170
	v_lshlrev_b64 v[166:167], 6, v[170:171]
	v_lshl_add_u64 v[166:167], v[136:137], 0, v[166:167]
	s_waitcnt vmcnt(8)
	v_add_f32_e32 v172, v176, v177
	v_add_f32_e32 v173, v178, v179
	v_add_f32_e32 v144, v172, v173
	ds_bpermute_b32 v157, v164, v144
	v_lshlrev_b64 v[166:167], 11, v[170:171]
	v_lshl_add_u64 v[170:171], v[142:143], 0, v[166:167]
	s_waitcnt lgkmcnt(0)
	v_add_f32_e32 v144, v144, v157
	ds_bpermute_b32 v157, v165, v144
	s_waitcnt lgkmcnt(0)
	v_add_f32_e32 v144, v144, v157
	v_fmamk_f32 v144, v144, 0x3a800000, v201
	v_rsq_f32_e32 v144, v144
	s_nop 0
	v_pk_mul_f32 v[110:111], v[110:111], v[144:145] op_sel_hi:[1,0]
	v_pk_mul_f32 v[108:109], v[108:109], v[144:145] op_sel_hi:[1,0]
	v_pk_mul_f32 v[106:107], v[106:107], v[144:145] op_sel_hi:[1,0]
	v_pk_mul_f32 v[104:105], v[104:105], v[144:145] op_sel_hi:[1,0]
	v_cvt_pk_bf16_f32 v166, v108, v109
	v_cvt_pk_bf16_f32 v167, v110, v111
	v_cvt_pk_bf16_f32 v168, v104, v105
	v_cvt_pk_bf16_f32 v169, v106, v107
	v_pk_mul_f32 v[102:103], v[102:103], v[144:145] op_sel_hi:[1,0]
	v_pk_mul_f32 v[100:101], v[100:101], v[144:145] op_sel_hi:[1,0]
	v_pk_mul_f32 v[98:99], v[98:99], v[144:145] op_sel_hi:[1,0]
	v_pk_mul_f32 v[96:97], v[96:97], v[144:145] op_sel_hi:[1,0]
	global_store_dwordx4 v[170:171], v[166:169], off
	s_nop 1
	v_cvt_pk_bf16_f32 v166, v100, v101
	v_cvt_pk_bf16_f32 v167, v102, v103
	v_cvt_pk_bf16_f32 v168, v96, v97
	v_cvt_pk_bf16_f32 v169, v98, v99
	global_store_dwordx4 v[170:171], v[166:169], off offset:256
	v_or_b32_e32 v170, 32, v156
	v_ashrrev_i32_e32 v171, 31, v170
	v_lshlrev_b64 v[166:167], 6, v[170:171]
	v_lshl_add_u64 v[166:167], v[136:137], 0, v[166:167]
	s_waitcnt vmcnt(9)
	v_add_f32_e32 v172, v180, v181
	v_add_f32_e32 v173, v182, v183
	v_add_f32_e32 v144, v172, v173
	ds_bpermute_b32 v157, v164, v144
	v_lshlrev_b64 v[166:167], 11, v[170:171]
	v_lshl_add_u64 v[170:171], v[142:143], 0, v[166:167]
	s_waitcnt lgkmcnt(0)
	v_add_f32_e32 v144, v144, v157
	ds_bpermute_b32 v157, v165, v144
	s_waitcnt lgkmcnt(0)
	v_add_f32_e32 v144, v144, v157
	v_fmamk_f32 v144, v144, 0x3a800000, v201
	v_rsq_f32_e32 v144, v144
	s_nop 0
	v_pk_mul_f32 v[94:95], v[94:95], v[144:145] op_sel_hi:[1,0]
	v_pk_mul_f32 v[92:93], v[92:93], v[144:145] op_sel_hi:[1,0]
	v_pk_mul_f32 v[90:91], v[90:91], v[144:145] op_sel_hi:[1,0]
	v_pk_mul_f32 v[88:89], v[88:89], v[144:145] op_sel_hi:[1,0]
	v_cvt_pk_bf16_f32 v166, v92, v93
	v_cvt_pk_bf16_f32 v167, v94, v95
	v_cvt_pk_bf16_f32 v168, v88, v89
	v_cvt_pk_bf16_f32 v169, v90, v91
	v_pk_mul_f32 v[86:87], v[86:87], v[144:145] op_sel_hi:[1,0]
	v_pk_mul_f32 v[84:85], v[84:85], v[144:145] op_sel_hi:[1,0]
	v_pk_mul_f32 v[82:83], v[82:83], v[144:145] op_sel_hi:[1,0]
	v_pk_mul_f32 v[80:81], v[80:81], v[144:145] op_sel_hi:[1,0]
	global_store_dwordx4 v[170:171], v[166:169], off
	s_nop 1
	v_cvt_pk_bf16_f32 v166, v84, v85
	v_cvt_pk_bf16_f32 v167, v86, v87
	v_cvt_pk_bf16_f32 v168, v80, v81
	v_cvt_pk_bf16_f32 v169, v82, v83
	global_store_dwordx4 v[170:171], v[166:169], off offset:256
	v_or_b32_e32 v170, 48, v156
	v_ashrrev_i32_e32 v171, 31, v170
	v_lshlrev_b64 v[166:167], 6, v[170:171]
	v_lshl_add_u64 v[166:167], v[136:137], 0, v[166:167]
	s_waitcnt vmcnt(10)
; __device__ __forceinline__ u32x2 pack4(f32x4 v) { u32x2 w; w.x = cvt_pk_bf16(v[0], v[1]); w.y = cvt_pk_bf16(v[2], v[3]); return w; }
; __device__ __forceinline__ float rstd_row4(const float* ssrow, int fq) { const f32x4 a = *(const f32x4*)(ssrow + 4 * fq); float ss = (a[0] + a[1]) + (a[2] + a[3]);
;     ss += __shfl_xor(ss, 16); ss += __shfl_xor(ss, 32); return __builtin_amdgcn_rsqf(ss * (1.0f / 1024.0f) + 1e-6f); }
;     __device__ __forceinline__ void operator()(const f32x4 (&acc)[2][2][4][2], const Unit& u, int wr, int wc, int fr, int fq) const {
;     ...
;         for (int ai = 0; ai < 2; ++ai)
; #pragma unroll
;             for (int m = 0; m < 4; ++m) {
;                 const int row = u.pm * BM + ai * HALF + wr * 64 + m * 16 + fr; const float rs = rstd_row4(ss + (size_t)row * 16, fq);
;                 bf16_t* rowp = base + (size_t)row * 1024 + cc;
; #pragma unroll
;                 for (int bj = 0; bj < 2; ++bj) { const f32x4 v0 = acc[ai][bj][m][0] * rs, v1 = acc[ai][bj][m][1] * rs; const u32x2 p0 = pack4(v0), p1 = pack4(v1);
;                     u32x4 w; w.x = p0.x; w.y = p0.y; w.z = p1.x; w.w = p1.y; *(u32x4*)(rowp + bj * HALF) = w; cs[bj][0] = cs[bj][0] + v0; cs[bj][1] = cs[bj][1] + v1; }
	v_add_f32_e32 v172, v184, v185
	v_add_f32_e32 v173, v186, v187
	v_add_f32_e32 v144, v172, v173
	ds_bpermute_b32 v157, v164, v144
	v_lshlrev_b64 v[166:167], 11, v[170:171]
	v_lshl_add_u64 v[170:171], v[142:143], 0, v[166:167]
	s_waitcnt lgkmcnt(0)
	v_add_f32_e32 v144, v144, v157
	ds_bpermute_b32 v157, v165, v144
	s_waitcnt lgkmcnt(0)
	v_add_f32_e32 v144, v144, v157
	v_fmamk_f32 v144, v144, 0x3a800000, v201
	v_rsq_f32_e32 v144, v144
	s_nop 0
	v_pk_mul_f32 v[78:79], v[78:79], v[144:145] op_sel_hi:[1,0]
	v_pk_mul_f32 v[76:77], v[76:77], v[144:145] op_sel_hi:[1,0]
	v_pk_mul_f32 v[74:75], v[74:75], v[144:145] op_sel_hi:[1,0]
	v_pk_mul_f32 v[72:73], v[72:73], v[144:145] op_sel_hi:[1,0]
	v_cvt_pk_bf16_f32 v166, v76, v77
	v_cvt_pk_bf16_f32 v167, v78, v79
	v_cvt_pk_bf16_f32 v168, v72, v73
	v_cvt_pk_bf16_f32 v169, v74, v75
	v_pk_mul_f32 v[70:71], v[70:71], v[144:145] op_sel_hi:[1,0]
	v_pk_mul_f32 v[68:69], v[68:69], v[144:145] op_sel_hi:[1,0]
	v_pk_mul_f32 v[66:67], v[66:67], v[144:145] op_sel_hi:[1,0]
	v_pk_mul_f32 v[64:65], v[64:65], v[144:145] op_sel_hi:[1,0]
	global_store_dwordx4 v[170:171], v[166:169], off
	s_nop 1
	v_cvt_pk_bf16_f32 v166, v68, v69
	v_cvt_pk_bf16_f32 v167, v70, v71
	v_cvt_pk_bf16_f32 v168, v64, v65
	v_cvt_pk_bf16_f32 v169, v66, v67
	global_store_dwordx4 v[170:171], v[166:169], off offset:256
	v_add_u32_e32 v170, 0x80, v156
	v_ashrrev_i32_e32 v171, 31, v170
	v_lshlrev_b64 v[166:167], 6, v[170:171]
	v_lshl_add_u64 v[166:167], v[136:137], 0, v[166:167]
	s_waitcnt vmcnt(11)
	v_add_f32_e32 v172, v188, v189
	v_add_f32_e32 v173, v190, v191
	v_add_f32_e32 v144, v172, v173
	ds_bpermute_b32 v157, v164, v144
	v_lshlrev_b64 v[166:167], 11, v[170:171]
	v_lshl_add_u64 v[170:171], v[142:143], 0, v[166:167]
	s_waitcnt lgkmcnt(0)
	v_add_f32_e32 v144, v144, v157
	ds_bpermute_b32 v157, v165, v144
	s_waitcnt lgkmcnt(0)
	v_add_f32_e32 v144, v144, v157
	v_fmamk_f32 v144, v144, 0x3a800000, v201
	v_rsq_f32_e32 v144, v144
	s_nop 0
	v_pk_mul_f32 v[62:63], v[62:63], v[144:145] op_sel_hi:[1,0]
	v_pk_mul_f32 v[60:61], v[60:61], v[144:145] op_sel_hi:[1,0]
	v_pk_mul_f32 v[58:59], v[58:59], v[144:145] op_sel_hi:[1,0]
	v_pk_mul_f32 v[56:57], v[56:57], v[144:145] op_sel_hi:[1,0]
	v_cvt_pk_bf16_f32 v166, v60, v61
	v_cvt_pk_bf16_f32 v167, v62, v63
	v_cvt_pk_bf16_f32 v168, v56, v57
	v_cvt_pk_bf16_f32 v169, v58, v59
	v_pk_mul_f32 v[54:55], v[54:55], v[144:145] op_sel_hi:[1,0]
	v_pk_mul_f32 v[52:53], v[52:53], v[144:145] op_sel_hi:[1,0]
	v_pk_mul_f32 v[50:51], v[50:51], v[144:145] op_sel_hi:[1,0]
	v_pk_mul_f32 v[48:49], v[48:49], v[144:145] op_sel_hi:[1,0]
	global_store_dwordx4 v[170:171], v[166:169], off
	s_nop 1
	v_cvt_pk_bf16_f32 v166, v52, v53
	v_cvt_pk_bf16_f32 v167, v54, v55
	v_cvt_pk_bf16_f32 v168, v48, v49
	v_cvt_pk_bf16_f32 v169, v50, v51
	global_store_dwordx4 v[170:171], v[166:169], off offset:256
	v_add_u32_e32 v170, 0x90, v156
	v_ashrrev_i32_e32 v171, 31, v170
	v_lshlrev_b64 v[166:167], 6, v[170:171]
	v_lshl_add_u64 v[166:167], v[136:137], 0, v[166:167]
	s_waitcnt vmcnt(12)
	v_add_f32_e32 v172, v192, v193
	v_add_f32_e32 v173, v194, v195
	v_add_f32_e32 v144, v172, v173
	ds_bpermute_b32 v157, v164, v144
	v_lshlrev_b64 v[166:167], 11, v[170:171]
	v_lshl_add_u64 v[170:171], v[142:143], 0, v[166:167]
	s_waitcnt lgkmcnt(0)
	v_add_f32_e32 v144, v144, v157
	ds_bpermute_b32 v157, v165, v144
	s_waitcnt lgkmcnt(0)
	v_add_f32_e32 v144, v144, v157
	v_fmamk_f32 v144, v144, 0x3a800000, v201
	v_rsq_f32_e32 v144, v144
	s_nop 0
	v_pk_mul_f32 v[46:47], v[46:47], v[144:145] op_sel_hi:[1,0]
	v_pk_mul_f32 v[44:45], v[44:45], v[144:145] op_sel_hi:[1,0]
	v_pk_mul_f32 v[42:43], v[42:43], v[144:145] op_sel_hi:[1,0]
	v_pk_mul_f32 v[40:41], v[40:41], v[144:145] op_sel_hi:[1,0]
	v_cvt_pk_bf16_f32 v166, v44, v45
	v_cvt_pk_bf16_f32 v167, v46, v47
	v_cvt_pk_bf16_f32 v168, v40, v41
	v_cvt_pk_bf16_f32 v169, v42, v43
	v_pk_mul_f32 v[38:39], v[38:39], v[144:145] op_sel_hi:[1,0]
	v_pk_mul_f32 v[36:37], v[36:37], v[144:145] op_sel_hi:[1,0]
	v_pk_mul_f32 v[34:35], v[34:35], v[144:145] op_sel_hi:[1,0]
	v_pk_mul_f32 v[32:33], v[32:33], v[144:145] op_sel_hi:[1,0]
	global_store_dwordx4 v[170:171], v[166:169], off
	s_nop 1
	v_cvt_pk_bf16_f32 v166, v36, v37
	v_cvt_pk_bf16_f32 v167, v38, v39
	v_cvt_pk_bf16_f32 v168, v32, v33
	v_cvt_pk_bf16_f32 v169, v34, v35
	global_store_dwordx4 v[170:171], v[166:169], off offset:256
	v_add_u32_e32 v170, 0xa0, v156
	v_ashrrev_i32_e32 v171, 31, v170
	v_lshlrev_b64 v[166:167], 6, v[170:171]
	v_lshl_add_u64 v[166:167], v[136:137], 0, v[166:167]
	v_add_u32_e32 v156, 0xb0, v156
	s_waitcnt vmcnt(13)
; __device__ __forceinline__ u32x2 pack4(f32x4 v) { u32x2 w; w.x = cvt_pk_bf16(v[0], v[1]); w.y = cvt_pk_bf16(v[2], v[3]); return w; }
;     __device__ __forceinline__ void operator()(const f32x4 (&acc)[2][2][4][2], const Unit& u, int wr, int wc, int fr, int fq) const {
;     ...
;         for (int ai = 0; ai < 2; ++ai)
; #pragma unroll
;             for (int m = 0; m < 4; ++m) {
;                 const int row = u.pm * BM + ai * HALF + wr * 64 + m * 16 + fr; const float rs = rstd_row4(ss + (size_t)row * 16, fq);
;                 bf16_t* rowp = base + (size_t)row * 1024 + cc;
; #pragma unroll
;                 for (int bj = 0; bj < 2; ++bj) { const f32x4 v0 = acc[ai][bj][m][0] * rs, v1 = acc[ai][bj][m][1] * rs; const u32x2 p0 = pack4(v0), p1 = pack4(v1);
;                     u32x4 w; w.x = p0.x; w.y = p0.y; w.z = p1.x; w.w = p1.y; *(u32x4*)(rowp + bj * HALF) = w; cs[bj][0] = cs[bj][0] + v0; cs[bj][1] = cs[bj][1] + v1; }
;             }
;         if (km) {
; #pragma unroll
;             for (int bj = 0; bj < 2; ++bj)
; #pragma unroll
;                 for (int n = 0; n < 2; ++n)
; #pragma unroll
;                     for (int i = 0; i < 4; ++i) { float v = cs[bj][n][i]; v += __shfl_xor(v, 1); v += __shfl_xor(v, 2); v += __shfl_xor(v, 4); v += __shfl_xor(v, 8);
;                         if (fr == 0) kmean[(size_t)(u.pm * 2 + wr) * 1024 + cc + bj * HALF + n * 4 + i] = v; }
	v_add_f32_e32 v172, v196, v197
	v_add_f32_e32 v173, v198, v199
	v_add_f32_e32 v144, v172, v173
	ds_bpermute_b32 v157, v164, v144
	v_lshlrev_b64 v[166:167], 11, v[170:171]
	v_lshl_add_u64 v[170:171], v[142:143], 0, v[166:167]
	s_waitcnt lgkmcnt(0)
	v_add_f32_e32 v144, v144, v157
	ds_bpermute_b32 v157, v165, v144
	s_waitcnt lgkmcnt(0)
	v_add_f32_e32 v144, v144, v157
	v_fmamk_f32 v144, v144, 0x3a800000, v201
	v_rsq_f32_e32 v144, v144
	v_ashrrev_i32_e32 v157, 31, v156
	v_pk_mul_f32 v[30:31], v[30:31], v[144:145] op_sel_hi:[1,0]
	v_pk_mul_f32 v[28:29], v[28:29], v[144:145] op_sel_hi:[1,0]
	v_pk_mul_f32 v[26:27], v[26:27], v[144:145] op_sel_hi:[1,0]
	v_pk_mul_f32 v[24:25], v[24:25], v[144:145] op_sel_hi:[1,0]
	v_cvt_pk_bf16_f32 v166, v28, v29
	v_cvt_pk_bf16_f32 v167, v30, v31
	v_cvt_pk_bf16_f32 v168, v24, v25
	v_cvt_pk_bf16_f32 v169, v26, v27
	v_pk_mul_f32 v[22:23], v[22:23], v[144:145] op_sel_hi:[1,0]
	v_pk_mul_f32 v[20:21], v[20:21], v[144:145] op_sel_hi:[1,0]
	v_pk_mul_f32 v[18:19], v[18:19], v[144:145] op_sel_hi:[1,0]
	v_pk_mul_f32 v[16:17], v[16:17], v[144:145] op_sel_hi:[1,0]
	global_store_dwordx4 v[170:171], v[166:169], off
	s_nop 1
	v_cvt_pk_bf16_f32 v166, v20, v21
	v_cvt_pk_bf16_f32 v167, v22, v23
	v_cvt_pk_bf16_f32 v168, v16, v17
	v_cvt_pk_bf16_f32 v169, v18, v19
	global_store_dwordx4 v[170:171], v[166:169], off offset:256
	s_nop 1
	v_lshlrev_b64 v[166:167], 6, v[156:157]
	v_lshl_add_u64 v[166:167], v[136:137], 0, v[166:167]
	v_lshlrev_b64 v[156:157], 11, v[156:157]
	v_lshl_add_u64 v[156:157], v[142:143], 0, v[156:157]
	s_waitcnt vmcnt(14)
	v_add_f32_e32 v170, v216, v217
	v_add_f32_e32 v171, v218, v219
	v_add_f32_e32 v144, v170, v171
	ds_bpermute_b32 v164, v164, v144
	s_waitcnt lgkmcnt(0)
	v_add_f32_e32 v144, v144, v164
	ds_bpermute_b32 v164, v165, v144
	s_waitcnt lgkmcnt(0)
	v_add_f32_e32 v144, v144, v164
	v_fmamk_f32 v144, v144, 0x3a800000, v201
	v_rsq_f32_e32 v144, v144
	s_nop 0
	v_pk_mul_f32 v[14:15], v[14:15], v[144:145] op_sel_hi:[1,0]
	v_pk_mul_f32 v[142:143], v[12:13], v[144:145] op_sel_hi:[1,0]
	v_pk_mul_f32 v[10:11], v[10:11], v[144:145] op_sel_hi:[1,0]
	v_pk_mul_f32 v[12:13], v[8:9], v[144:145] op_sel_hi:[1,0]
	v_cvt_pk_bf16_f32 v164, v142, v143
	v_cvt_pk_bf16_f32 v165, v14, v15
	v_cvt_pk_bf16_f32 v166, v12, v13
	v_cvt_pk_bf16_f32 v167, v10, v11
	v_pk_mul_f32 v[6:7], v[6:7], v[144:145] op_sel_hi:[1,0]
	v_pk_mul_f32 v[4:5], v[4:5], v[144:145] op_sel_hi:[1,0]
	v_pk_mul_f32 v[2:3], v[2:3], v[144:145] op_sel_hi:[1,0]
	v_pk_mul_f32 v[0:1], v[0:1], v[144:145] op_sel_hi:[1,0]
	global_store_dwordx4 v[156:157], v[164:167], off
	s_nop 1
	v_cvt_pk_bf16_f32 v164, v4, v5
	v_cvt_pk_bf16_f32 v165, v6, v7
	v_cvt_pk_bf16_f32 v166, v0, v1
	v_cvt_pk_bf16_f32 v167, v2, v3
	global_store_dwordx4 v[156:157], v[164:167], off offset:256
	s_cbranch_vccnz .LBB0_405
	v_pk_add_f32 v[8:9], v[124:125], 0 op_sel_hi:[1,0]
	s_lshl_b32 s13, s28, 1
	v_pk_add_f32 v[8:9], v[8:9], v[108:109]
	s_add_i32 s28, s13, s50
	v_pk_add_f32 v[8:9], v[8:9], v[92:93]
	s_ashr_i32 s29, s28, 31
	v_pk_add_f32 v[8:9], v[8:9], v[76:77]
	s_lshl_b64 s[28:29], s[28:29], 12
	v_pk_add_f32 v[8:9], v[8:9], v[60:61]
	v_readlane_b32 s40, v255, 14
	v_pk_add_f32 v[8:9], v[8:9], v[44:45]
	v_readlane_b32 s41, v255, 15
	v_pk_add_f32 v[8:9], v[8:9], v[28:29]
	s_add_u32 s28, s40, s28
	v_pk_add_f32 v[28:29], v[8:9], v[142:143]
	v_xor_b32_e32 v8, 1, v203
	v_cmp_lt_i32_e32 vcc, v8, v163
	v_xor_b32_e32 v9, 4, v203
	s_addc_u32 s29, s41, s29
	v_cndmask_b32_e32 v8, v203, v8, vcc
	v_lshlrev_b32_e32 v44, 2, v8
	v_xor_b32_e32 v8, 2, v203
	v_cmp_lt_i32_e32 vcc, v8, v163
	v_lshlrev_b32_e32 v144, 2, v162
	s_nop 0
	v_cndmask_b32_e32 v8, v203, v8, vcc
	v_lshlrev_b32_e32 v45, 2, v8
	ds_bpermute_b32 v8, v44, v28
	v_cmp_lt_i32_e32 vcc, v9, v163
	s_waitcnt lgkmcnt(0)
	v_add_f32_e32 v8, v28, v8
	v_cndmask_b32_e32 v9, v203, v9, vcc
	v_lshlrev_b32_e32 v60, 2, v9
	ds_bpermute_b32 v9, v45, v8
	v_xor_b32_e32 v28, 8, v203
	v_cmp_lt_i32_e32 vcc, v28, v163
	s_waitcnt lgkmcnt(0)
	v_add_f32_e32 v8, v8, v9
	ds_bpermute_b32 v9, v60, v8
	v_cndmask_b32_e32 v28, v203, v28, vcc
	v_lshlrev_b32_e32 v28, 2, v28
	s_waitcnt lgkmcnt(0)
	v_add_f32_e32 v61, v8, v9
	ds_bpermute_b32 v76, v28, v61
	v_lshl_add_u64 v[8:9], s[28:29], 0, v[144:145]
	s_and_saveexec_b64 s[28:29], s[36:37]
	s_cbranch_execz .LBB0_374
	s_waitcnt lgkmcnt(0)
	v_add_f32_e32 v61, v61, v76
	global_store_dword v[8:9], v61, off
